# v22 + compress loop: rotary pairs via 4 v_mul_f32 from the cos/sin registers instead of 4 v_mov + 2 v_pk_mul_f32 + nop (same f32 products)
# speedup vs baseline: 1.0052x; 1.0052x over previous
; #define LAS __attribute__((address_space(3)))
; DI void unpack8(const v4u u, float (&f)[8]) { f[0] = bflo(u.x); f[1] = bfhi(u.x); f[2] = bflo(u.y); f[3] = bfhi(u.y); f[4] = bflo(u.z); f[5] = bfhi(u.z); f[6] = bflo(u.w); f[7] = bfhi(u.w); }
; DI v4u pack8(const float (&f)[8]) { v4u o; o.x = pk2(f[0], f[1]); o.y = pk2(f[2], f[3]); o.z = pk2(f[4], f[5]); o.w = pk2(f[6], f[7]); return o; }
; #define CMP_LOADB(dst, ll_) do { _Pragma("unroll") for (int ks = 0; ks < 2; ++ks) _Pragma("unroll") for (int ct = 0; ct < 2; ++ct) dst[ks][ct] = *(const bf16x8*)(W1T + (size_t)(32 * w + 16 * ct + fr) * 2048 + (ll_) * 64 + ks * 32 + fq * 8); } while (0)
; DI void nsa_compress_item(KA a, const int l, LAS unsigned char* lds, const int it) {
;     ...
;     CMP_LOADA(0); CMP_LOADB(bcur, 0);
;     for (int ll = 0; ll < 32; ++ll) {
;         __syncthreads();
;         if (stager) { float x1[8], x2[8], o1[8], o2[8]; unpack8(xr1, x1); unpack8(xr2, x2);
; #pragma unroll
;             for (int e = 0; e < 8; ++e) { float y1 = svalid ? x1[e] : 0.f, y2 = svalid ? x2[e] : 0.f;
;                 if (kv == 0 && svalid) { const float cc = cs[e >> 2][e & 3], ss = sn[e >> 2][e & 3]; y1 = x1[e] * cc - x2[e] * ss; y2 = x1[e] * ss + x2[e] * cc; }
;                 o1[e] = y1 + ps1[e >> 2][e & 3]; o2[e] = y2 + ps2[e >> 2][e & 3]; }
;             *(LAS v4u*)(At + sc_ * PA + 8 * sm_) = pack8(o1); *(LAS v4u*)(At + sc_ * PA + 32 + 8 * sm_) = pack8(o2); }
.LBB0_480:
	v_lshl_add_u64 v[132:133], s[56:57], 1, v[98:99]
	v_lshl_add_u64 v[134:135], v[132:133], 0, v[100:101]
	v_lshl_add_u64 v[132:133], v[132:133], 0, v[102:103]
	global_load_dwordx4 v[136:139], v[134:135], off
	global_load_dwordx4 v[140:143], v[132:133], off
	global_load_dwordx4 v[144:147], v[134:135], off offset:64
	global_load_dwordx4 v[148:151], v[132:133], off offset:64
	s_and_saveexec_b64 s[58:59], s[2:3]
	s_cbranch_execz .LBB0_482
	s_waitcnt vmcnt(8)
	v_lshlrev_b32_e32 v89, 16, v4
	v_lshlrev_b32_e32 v88, 16, v0
	v_mul_f32_e32 v90, v16, v88
	v_mul_f32_e32 v91, v20, v89
	v_sub_f32_e32 v92, v90, v91
	v_mul_f32_e32 v90, v20, v88
	v_mul_f32_e32 v91, v16, v89
	v_cndmask_b32_e64 v88, v88, v92, s[40:41]
	v_add_f32_e32 v90, v90, v91
	v_cndmask_b32_e64 v89, v89, v90, s[40:41]
	v_cndmask_b32_e64 v89, 0, v89, s[0:1]
	v_cndmask_b32_e64 v88, 0, v88, s[0:1]
	s_waitcnt vmcnt(6)
	v_add_f32_e32 v92, v36, v88
	s_waitcnt vmcnt(4)
	v_add_f32_e32 v93, v52, v89
	v_and_b32_e32 v89, 0xffff0000, v4
	v_and_b32_e32 v88, 0xffff0000, v0
	v_mul_f32_e32 v90, v17, v88
	v_mul_f32_e32 v91, v21, v89
	v_sub_f32_e32 v94, v90, v91
	v_mul_f32_e32 v90, v21, v88
	v_mul_f32_e32 v91, v17, v89
	v_cndmask_b32_e64 v88, v88, v94, s[40:41]
	v_add_f32_e32 v90, v90, v91
	v_cndmask_b32_e64 v89, v89, v90, s[40:41]
	v_cndmask_b32_e64 v89, 0, v89, s[0:1]
	v_cndmask_b32_e64 v88, 0, v88, s[0:1]
	v_add_f32_e32 v94, v37, v88
	v_add_f32_e32 v95, v53, v89
	v_lshlrev_b32_e32 v89, 16, v5
	v_lshlrev_b32_e32 v88, 16, v1
	v_mul_f32_e32 v90, v18, v88
	v_mul_f32_e32 v91, v22, v89
	v_sub_f32_e32 v113, v90, v91
	v_mul_f32_e32 v90, v22, v88
	v_mul_f32_e32 v91, v18, v89
	v_cndmask_b32_e64 v88, v88, v113, s[40:41]
	v_add_f32_e32 v90, v90, v91
	v_cndmask_b32_e64 v89, v89, v90, s[40:41]
	v_cndmask_b32_e64 v89, 0, v89, s[0:1]
	v_cndmask_b32_e64 v88, 0, v88, s[0:1]
	v_add_f32_e32 v113, v38, v88
	v_add_f32_e32 v115, v54, v89
	v_and_b32_e32 v89, 0xffff0000, v5
	v_and_b32_e32 v88, 0xffff0000, v1
	v_mul_f32_e32 v90, v19, v88
	v_mul_f32_e32 v91, v23, v89
	v_sub_f32_e32 v122, v90, v91
	v_mul_f32_e32 v90, v23, v88
	v_mul_f32_e32 v91, v19, v89
	v_cndmask_b32_e64 v88, v88, v122, s[40:41]
	v_add_f32_e32 v90, v90, v91
	v_cndmask_b32_e64 v89, v89, v90, s[40:41]
	v_cndmask_b32_e64 v89, 0, v89, s[0:1]
	v_cndmask_b32_e64 v88, 0, v88, s[0:1]
	v_add_f32_e32 v122, v39, v88
	v_add_f32_e32 v123, v55, v89
	v_lshlrev_b32_e32 v89, 16, v6
	v_lshlrev_b32_e32 v88, 16, v2
	v_mul_f32_e32 v90, v8, v88
	v_mul_f32_e32 v91, v12, v89
	v_sub_f32_e32 v124, v90, v91
	v_mul_f32_e32 v90, v12, v88
	v_mul_f32_e32 v91, v8, v89
	v_cndmask_b32_e64 v88, v88, v124, s[40:41]
	v_add_f32_e32 v90, v90, v91
	v_cndmask_b32_e64 v89, v89, v90, s[40:41]
	v_cndmask_b32_e64 v89, 0, v89, s[0:1]
	v_cndmask_b32_e64 v88, 0, v88, s[0:1]
	v_add_f32_e32 v124, v24, v88
	v_add_f32_e32 v125, v28, v89
	v_and_b32_e32 v89, 0xffff0000, v6
	v_and_b32_e32 v88, 0xffff0000, v2
	v_mul_f32_e32 v90, v9, v88
	v_mul_f32_e32 v91, v13, v89
	v_sub_f32_e32 v126, v90, v91
	v_mul_f32_e32 v90, v13, v88
	v_mul_f32_e32 v91, v9, v89
	v_cndmask_b32_e64 v88, v88, v126, s[40:41]
	v_add_f32_e32 v90, v90, v91
	v_cndmask_b32_e64 v89, v89, v90, s[40:41]
	v_cndmask_b32_e64 v89, 0, v89, s[0:1]
	v_cndmask_b32_e64 v88, 0, v88, s[0:1]
	v_add_f32_e32 v126, v25, v88
	v_add_f32_e32 v127, v29, v89
	v_lshlrev_b32_e32 v89, 16, v7
	v_lshlrev_b32_e32 v88, 16, v3
	v_mul_f32_e32 v90, v10, v88
	v_mul_f32_e32 v91, v14, v89
	v_sub_f32_e32 v128, v90, v91
	v_mul_f32_e32 v90, v14, v88
	v_mul_f32_e32 v91, v10, v89
	v_cndmask_b32_e64 v88, v88, v128, s[40:41]
	v_add_f32_e32 v90, v90, v91
	v_cndmask_b32_e64 v89, v89, v90, s[40:41]
	v_cndmask_b32_e64 v89, 0, v89, s[0:1]
	v_cndmask_b32_e64 v88, 0, v88, s[0:1]
	v_add_f32_e32 v128, v26, v88
	v_add_f32_e32 v129, v30, v89
	v_and_b32_e32 v89, 0xffff0000, v7
	v_and_b32_e32 v88, 0xffff0000, v3
	v_mul_f32_e32 v90, v11, v88
	v_mul_f32_e32 v91, v15, v89
	v_sub_f32_e32 v130, v90, v91
	v_mul_f32_e32 v90, v15, v88
	v_mul_f32_e32 v91, v11, v89
	v_cndmask_b32_e64 v88, v88, v130, s[40:41]
	v_add_f32_e32 v90, v90, v91
	v_cndmask_b32_e64 v89, v89, v90, s[40:41]
	v_cndmask_b32_e64 v88, 0, v88, s[0:1]
	v_cndmask_b32_e64 v89, 0, v89, s[0:1]
	v_add_f32_e32 v91, v27, v88
	v_add_f32_e32 v130, v31, v89
	v_cvt_pk_bf16_f32 v88, v92, v94
	v_cvt_pk_bf16_f32 v89, v113, v122
	v_cvt_pk_bf16_f32 v90, v124, v126
	v_cvt_pk_bf16_f32 v91, v128, v91
	ds_write_b128 v121, v[88:91]
	v_cvt_pk_bf16_f32 v88, v93, v95
	v_cvt_pk_bf16_f32 v89, v115, v123
	v_cvt_pk_bf16_f32 v90, v125, v127
	v_cvt_pk_bf16_f32 v91, v129, v130
	ds_write_b128 v121, v[88:91] offset:64
